# in-proj QK epilogue: compiler-emitted vmcnt waits recounted to include the write-through stores hidden in inline asm (loads no longer wait behind younger stores)
# baseline (speedup 1.0000x reference)
.LBB0_334:
	s_lshl_b32 s28, s34, 6
	s_ashr_i32 s29, s28, 31
	v_lshlrev_b32_e32 v120, 6, v194
	v_and_b32_e32 v189, 0x3f3c0, v120
	v_lshl_add_u64 v[120:121], s[28:29], 2, v[158:159]
	global_load_dwordx4 v[200:203], v189, s[84:85] offset:32
	global_load_dwordx4 v[132:135], v[120:121], off
	global_load_dwordx4 v[128:131], v[120:121], off offset:16
	global_load_dwordx4 v[124:127], v[120:121], off offset:128
	s_nop 0
	global_load_dwordx4 v[120:123], v[120:121], off offset:144
	s_nop 0
	global_load_dwordx4 v[204:207], v189, s[84:85]
	v_pk_mul_f32 v[222:223], v[140:141], v[198:199] op_sel_hi:[1,0]
	v_pk_mul_f32 v[226:227], v[138:139], v[198:199] op_sel_hi:[1,0]
	global_load_dwordx4 v[138:141], v189, s[84:85] offset:16
	global_load_dwordx4 v[208:211], v189, s[84:85] offset:48
	v_pk_mul_f32 v[142:143], v[142:143], v[198:199] op_sel_hi:[1,0]
	v_pk_mul_f32 v[228:229], v[136:137], v[198:199] op_sel_hi:[1,0]
	v_pk_mul_f32 v[230:231], v[118:119], v[198:199] op_sel_hi:[1,0]
	v_pk_mul_f32 v[232:233], v[116:117], v[198:199] op_sel_hi:[1,0]
	v_pk_mul_f32 v[234:235], v[114:115], v[198:199] op_sel_hi:[1,0]
	v_pk_mul_f32 v[198:199], v[112:113], v[198:199] op_sel_hi:[1,0]
	v_pk_mul_f32 v[112:113], v[142:143], v[142:143]
	v_pk_mul_f32 v[114:115], v[222:223], v[222:223]
	v_pk_mul_f32 v[116:117], v[226:227], v[226:227]
	v_pk_mul_f32 v[118:119], v[228:229], v[228:229]
	v_pk_mov_b32 v[218:219], v[114:115], v[112:113] op_sel:[1,0]
	v_mov_b32_e32 v115, v113
	v_pk_mov_b32 v[112:113], v[118:119], v[116:117] op_sel:[1,0]
	v_mov_b32_e32 v119, v117
	v_pk_add_f32 v[114:115], v[218:219], v[114:115]
	v_pk_add_f32 v[112:113], v[112:113], v[118:119]
	v_pk_mul_f32 v[136:137], v[230:231], v[230:231]
	v_pk_mul_f32 v[212:213], v[232:233], v[232:233]
	v_pk_mul_f32 v[214:215], v[234:235], v[234:235]
	v_pk_mul_f32 v[216:217], v[198:199], v[198:199]
	v_pk_add_f32 v[114:115], v[114:115], v[114:115] op_sel_hi:[0,1]
	v_pk_add_f32 v[112:113], v[112:113], v[112:113] op_sel_hi:[0,1]
	v_add_f32_e32 v117, v212, v213
	v_add_f32_e32 v137, v136, v137
	v_mov_b32_e32 v116, v216
	v_mov_b32_e32 v136, v217
	v_mov_b32_e32 v114, v214
	v_mov_b32_e32 v112, v215
	v_pk_add_f32 v[116:117], v[116:117], v[136:137]
	v_pk_add_f32 v[112:113], v[114:115], v[112:113]
	v_lshl_add_u64 v[136:137], s[60:61], 0, v[220:221]
	v_pk_add_f32 v[112:113], v[116:117], v[112:113]
	s_lshl_b32 s4, s35, 16
	v_add_f32_e32 v112, v112, v113
	ds_bpermute_b32 v113, v181, v112
	s_or_b32 s20, s4, s45
	v_lshl_add_u64 v[194:195], v[194:195], 0, s[20:21]
	v_lshlrev_b64 v[194:195], 7, v[194:195]
	v_lshl_add_u64 v[194:195], v[136:137], 0, v[194:195]
	s_waitcnt lgkmcnt(0)
	v_add_f32_e32 v112, v112, v113
	ds_bpermute_b32 v113, v185, v112
	v_pk_mul_f32 v[78:79], v[78:79], v[188:189] op_sel_hi:[1,0]
	v_pk_mul_f32 v[14:15], v[14:15], v[172:173] op_sel_hi:[1,0]
	v_pk_mul_f32 v[12:13], v[12:13], v[172:173] op_sel_hi:[1,0]
	v_pk_mul_f32 v[10:11], v[10:11], v[172:173] op_sel_hi:[1,0]
	s_waitcnt lgkmcnt(0)
	v_add_f32_e32 v112, v112, v113
	v_fmamk_f32 v112, v112, 0x3c800000, v241
	v_rsq_f32_e32 v220, v112
	global_load_dwordx4 v[112:115], v189, s[84:85] offset:1072
	global_load_dwordx4 v[212:215], v189, s[84:85] offset:1056
	global_load_dwordx4 v[116:119], v189, s[84:85] offset:1040
	global_load_dwordx4 v[216:219], v189, s[84:85] offset:1024
	v_pk_mul_f32 v[8:9], v[8:9], v[172:173] op_sel_hi:[1,0]
	v_pk_mul_f32 v[6:7], v[6:7], v[172:173] op_sel_hi:[1,0]
	v_pk_mul_f32 v[142:143], v[142:143], v[220:221] op_sel_hi:[1,0]
	v_pk_mul_f32 v[222:223], v[222:223], v[220:221] op_sel_hi:[1,0]
	v_pk_mul_f32 v[228:229], v[228:229], v[220:221] op_sel_hi:[1,0]
	v_pk_mul_f32 v[226:227], v[226:227], v[220:221] op_sel_hi:[1,0]
	v_pk_mul_f32 v[232:233], v[232:233], v[220:221] op_sel_hi:[1,0]
	v_pk_mul_f32 v[198:199], v[198:199], v[220:221] op_sel_hi:[1,0]
	v_pk_mul_f32 v[230:231], v[230:231], v[220:221] op_sel_hi:[1,0]
	v_pk_mul_f32 v[234:235], v[234:235], v[220:221] op_sel_hi:[1,0]
	v_pk_mul_f32 v[4:5], v[4:5], v[172:173] op_sel_hi:[1,0]
	s_waitcnt vmcnt(10)
	v_pk_mul_f32 v[142:143], v[134:135], v[142:143]
	ds_bpermute_b32 v238, v181, v142
	ds_bpermute_b32 v239, v181, v143
	v_pk_mul_f32 v[202:203], v[156:157], v[202:203]
	v_pk_mul_f32 v[222:223], v[132:133], v[222:223]
	s_waitcnt vmcnt(6)
	v_pk_mul_f32 v[206:207], v[206:207], v[142:143]
	v_pk_mul_f32 v[226:227], v[130:131], v[226:227]
	v_pk_mul_f32 v[228:229], v[128:129], v[228:229]
	ds_bpermute_b32 v236, v181, v222
	ds_bpermute_b32 v237, v181, v223
	s_waitcnt lgkmcnt(2)
	v_pk_fma_f32 v[202:203], v[202:203], v[238:239], v[206:207]
	ds_bpermute_b32 v242, v181, v228
	v_cndmask_b32_e64 v143, v143, v203, s[40:41]
	v_cndmask_b32_e64 v142, v142, v202, s[40:41]
	ds_bpermute_b32 v243, v181, v229
	ds_bpermute_b32 v202, v181, v226
	ds_bpermute_b32 v203, v181, v227
	v_pk_mul_f32 v[200:201], v[154:155], v[200:201]
	v_pk_mul_f32 v[204:205], v[204:205], v[222:223]
	s_waitcnt vmcnt(5)
	v_pk_mul_f32 v[138:139], v[138:139], v[228:229]
	s_waitcnt lgkmcnt(4)
	v_pk_fma_f32 v[200:201], v[200:201], v[236:237], v[204:205]
	v_pk_mul_f32 v[140:141], v[140:141], v[226:227]
	s_waitcnt vmcnt(4)
	v_pk_mul_f32 v[204:205], v[156:157], v[210:211]
	v_pk_mul_f32 v[206:207], v[154:155], v[208:209]
	s_waitcnt lgkmcnt(0)
	v_pk_fma_f32 v[140:141], v[204:205], v[202:203], v[140:141]
	v_pk_fma_f32 v[138:139], v[206:207], v[242:243], v[138:139]
	v_cndmask_b32_e64 v201, v223, v201, s[40:41]
	v_cndmask_b32_e64 v200, v222, v200, s[40:41]
	v_cndmask_b32_e64 v139, v229, v139, s[40:41]
	v_cndmask_b32_e64 v138, v228, v138, s[40:41]
	v_cndmask_b32_e64 v141, v227, v141, s[40:41]
	v_cndmask_b32_e64 v140, v226, v140, s[40:41]
	v_pk_mul_f32 v[142:143], v[168:169], v[142:143] op_sel_hi:[0,1]
	v_pk_mul_f32 v[200:201], v[168:169], v[200:201] op_sel_hi:[0,1]
	v_pk_mul_f32 v[202:203], v[168:169], v[140:141] op_sel_hi:[0,1]
	v_pk_mul_f32 v[140:141], v[168:169], v[138:139] op_sel_hi:[0,1]
	v_cvt_pk_bf16_f32 v138, v200, v201
	v_cvt_pk_bf16_f32 v139, v142, v143
	v_cvt_pk_bf16_f32 v140, v140, v141
	v_cvt_pk_bf16_f32 v141, v202, v203
	v_pk_mul_f32 v[142:143], v[110:111], v[196:197] op_sel_hi:[1,0]
	global_store_dwordx4 v[194:195], v[138:141], off sc1
	s_nop 2
	v_lshl_add_u64 v[138:139], v[194:195], 0, 64
	v_pk_mul_f32 v[194:195], v[108:109], v[196:197] op_sel_hi:[1,0]
	v_pk_mul_f32 v[108:109], v[142:143], v[142:143]
	v_pk_mul_f32 v[110:111], v[194:195], v[194:195]
	v_pk_mul_f32 v[202:203], v[104:105], v[196:197] op_sel_hi:[1,0]
	v_pk_mov_b32 v[200:201], v[110:111], v[108:109] op_sel:[1,0]
	v_mov_b32_e32 v111, v109
	v_pk_add_f32 v[108:109], v[200:201], v[110:111]
	v_pk_mul_f32 v[200:201], v[106:107], v[196:197] op_sel_hi:[1,0]
	v_pk_mul_f32 v[106:107], v[202:203], v[202:203]
	v_pk_mul_f32 v[104:105], v[200:201], v[200:201]
	v_pk_mul_f32 v[204:205], v[102:103], v[196:197] op_sel_hi:[1,0]
	v_pk_mov_b32 v[110:111], v[106:107], v[104:105] op_sel:[1,0]
	v_mov_b32_e32 v107, v105
	v_pk_add_f32 v[104:105], v[110:111], v[106:107]
	v_pk_mul_f32 v[206:207], v[100:101], v[196:197] op_sel_hi:[1,0]
	v_pk_mul_f32 v[208:209], v[98:99], v[196:197] op_sel_hi:[1,0]
	v_pk_mul_f32 v[196:197], v[96:97], v[196:197] op_sel_hi:[1,0]
	v_pk_add_f32 v[108:109], v[108:109], v[108:109] op_sel_hi:[0,1]
	v_pk_add_f32 v[104:105], v[104:105], v[104:105] op_sel_hi:[0,1]
	v_pk_mul_f32 v[100:101], v[204:205], v[204:205]
	v_pk_mul_f32 v[102:103], v[206:207], v[206:207]
	v_pk_mul_f32 v[96:97], v[208:209], v[208:209]
	v_pk_mul_f32 v[98:99], v[196:197], v[196:197]
	v_add_f32_e32 v103, v102, v103
	v_add_f32_e32 v101, v100, v101
	v_mov_b32_e32 v102, v98
	v_mov_b32_e32 v100, v99
	v_mov_b32_e32 v108, v96
	v_mov_b32_e32 v104, v97
	v_pk_add_f32 v[98:99], v[102:103], v[100:101]
	v_pk_add_f32 v[96:97], v[108:109], v[104:105]
	v_pk_mul_f32 v[232:233], v[124:125], v[232:233]
	v_pk_add_f32 v[96:97], v[98:99], v[96:97]
	v_pk_mul_f32 v[198:199], v[120:121], v[198:199]
	v_add_f32_e32 v102, v96, v97
	ds_bpermute_b32 v103, v181, v102
	v_pk_mul_f32 v[96:97], v[168:169], v[232:233] op_sel_hi:[0,1]
	v_pk_mul_f32 v[230:231], v[126:127], v[230:231]
	v_pk_mul_f32 v[234:235], v[122:123], v[234:235]
	v_pk_mul_f32 v[98:99], v[168:169], v[198:199] op_sel_hi:[0,1]
	s_waitcnt lgkmcnt(0)
	v_add_f32_e32 v102, v102, v103
	ds_bpermute_b32 v103, v185, v102
	v_cvt_pk_bf16_f32 v96, v96, v97
	v_pk_mul_f32 v[140:141], v[168:169], v[230:231] op_sel_hi:[0,1]
	v_pk_mul_f32 v[100:101], v[168:169], v[234:235] op_sel_hi:[0,1]
	v_cvt_pk_bf16_f32 v97, v140, v141
	v_cvt_pk_bf16_f32 v98, v98, v99
	v_cvt_pk_bf16_f32 v99, v100, v101
	s_waitcnt vmcnt(3)
	v_pk_mul_f32 v[214:215], v[156:157], v[214:215]
	global_store_dwordx4 v[138:139], v[96:99], off sc1
	s_nop 2
	s_waitcnt lgkmcnt(0)
	v_add_f32_e32 v96, v102, v103
	v_fmamk_f32 v96, v96, 0x3c800000, v241
	v_rsq_f32_e32 v138, v96
	global_load_dwordx4 v[96:99], v189, s[84:85] offset:2096
	global_load_dwordx4 v[100:103], v189, s[84:85] offset:2080
	global_load_dwordx4 v[104:107], v189, s[84:85] offset:2064
	global_load_dwordx4 v[108:111], v189, s[84:85] offset:2048
	v_pk_mul_f32 v[212:213], v[154:155], v[212:213]
	v_pk_mul_f32 v[114:115], v[156:157], v[114:115]
	v_pk_mul_f32 v[140:141], v[194:195], v[138:139] op_sel_hi:[1,0]
	v_pk_mul_f32 v[142:143], v[142:143], v[138:139] op_sel_hi:[1,0]
	v_pk_mul_f32 v[140:141], v[132:133], v[140:141]
	v_pk_mul_f32 v[142:143], v[134:135], v[142:143]
	v_pk_mul_f32 v[198:199], v[200:201], v[138:139] op_sel_hi:[1,0]
	v_pk_mul_f32 v[200:201], v[204:205], v[138:139] op_sel_hi:[1,0]
	v_pk_mul_f32 v[204:205], v[208:209], v[138:139] op_sel_hi:[1,0]
	v_pk_mul_f32 v[194:195], v[202:203], v[138:139] op_sel_hi:[1,0]
	v_pk_mul_f32 v[202:203], v[206:207], v[138:139] op_sel_hi:[1,0]
	v_pk_mul_f32 v[138:139], v[196:197], v[138:139] op_sel_hi:[1,0]
	v_pk_mul_f32 v[196:197], v[122:123], v[204:205]
	ds_bpermute_b32 v204, v181, v140
	ds_bpermute_b32 v205, v181, v141
	ds_bpermute_b32 v206, v181, v142
	ds_bpermute_b32 v207, v181, v143
	s_waitcnt vmcnt(6)
	v_pk_mul_f32 v[208:209], v[216:217], v[140:141]
	v_pk_mul_f32 v[210:211], v[218:219], v[142:143]
	v_pk_mul_f32 v[198:199], v[130:131], v[198:199]
	v_pk_mul_f32 v[194:195], v[128:129], v[194:195]
	s_waitcnt lgkmcnt(0)
	v_pk_fma_f32 v[206:207], v[214:215], v[206:207], v[210:211]
	v_pk_fma_f32 v[204:205], v[212:213], v[204:205], v[208:209]
	v_cndmask_b32_e64 v143, v143, v207, s[40:41]
	v_cndmask_b32_e64 v141, v141, v205, s[40:41]
	v_cndmask_b32_e64 v140, v140, v204, s[40:41]
	v_cndmask_b32_e64 v142, v142, v206, s[40:41]
	ds_bpermute_b32 v204, v181, v194
	ds_bpermute_b32 v205, v181, v195
	ds_bpermute_b32 v206, v181, v198
	ds_bpermute_b32 v207, v181, v199
	v_pk_mul_f32 v[116:117], v[116:117], v[194:195]
	v_pk_mul_f32 v[118:119], v[118:119], v[198:199]
	v_pk_mul_f32 v[112:113], v[154:155], v[112:113]
	v_pk_mul_f32 v[140:141], v[168:169], v[140:141] op_sel_hi:[0,1]
	s_waitcnt lgkmcnt(0)
	v_pk_fma_f32 v[114:115], v[114:115], v[206:207], v[118:119]
	v_pk_fma_f32 v[112:113], v[112:113], v[204:205], v[116:117]
	v_lshl_add_u64 v[116:117], v[190:191], 0, s[20:21]
	v_cndmask_b32_e64 v113, v195, v113, s[40:41]
	v_cndmask_b32_e64 v112, v194, v112, s[40:41]
	v_cndmask_b32_e64 v115, v199, v115, s[40:41]
	v_cndmask_b32_e64 v114, v198, v114, s[40:41]
	v_lshlrev_b64 v[116:117], 7, v[116:117]
	v_lshl_add_u64 v[116:117], v[136:137], 0, v[116:117]
	v_pk_mul_f32 v[118:119], v[168:169], v[142:143] op_sel_hi:[0,1]
	v_pk_mul_f32 v[142:143], v[168:169], v[114:115] op_sel_hi:[0,1]
	v_pk_mul_f32 v[114:115], v[168:169], v[112:113] op_sel_hi:[0,1]
	v_cvt_pk_bf16_f32 v112, v140, v141
	v_cvt_pk_bf16_f32 v113, v118, v119
	v_cvt_pk_bf16_f32 v114, v114, v115
	v_cvt_pk_bf16_f32 v115, v142, v143
	v_pk_mul_f32 v[118:119], v[92:93], v[192:193] op_sel_hi:[1,0]
	global_store_dwordx4 v[116:117], v[112:115], off sc1
	s_nop 2
	v_lshl_add_u64 v[112:113], v[116:117], 0, 64
	v_pk_mul_f32 v[116:117], v[94:95], v[192:193] op_sel_hi:[1,0]
	v_pk_mul_f32 v[94:95], v[118:119], v[118:119]
	v_pk_mul_f32 v[92:93], v[116:117], v[116:117]
	v_pk_mul_f32 v[142:143], v[88:89], v[192:193] op_sel_hi:[1,0]
	v_pk_mov_b32 v[140:141], v[94:95], v[92:93] op_sel:[1,0]
	v_mov_b32_e32 v95, v93
	v_pk_add_f32 v[92:93], v[140:141], v[94:95]
	v_pk_mul_f32 v[140:141], v[90:91], v[192:193] op_sel_hi:[1,0]
	v_pk_mul_f32 v[90:91], v[142:143], v[142:143]
	v_pk_mul_f32 v[88:89], v[140:141], v[140:141]
	v_pk_mul_f32 v[190:191], v[86:87], v[192:193] op_sel_hi:[1,0]
	v_pk_mov_b32 v[94:95], v[90:91], v[88:89] op_sel:[1,0]
	v_mov_b32_e32 v91, v89
	v_pk_add_f32 v[88:89], v[94:95], v[90:91]
	v_pk_mul_f32 v[194:195], v[84:85], v[192:193] op_sel_hi:[1,0]
	v_pk_mul_f32 v[198:199], v[82:83], v[192:193] op_sel_hi:[1,0]
	v_pk_mul_f32 v[192:193], v[80:81], v[192:193] op_sel_hi:[1,0]
	v_pk_add_f32 v[92:93], v[92:93], v[92:93] op_sel_hi:[0,1]
	v_pk_add_f32 v[88:89], v[88:89], v[88:89] op_sel_hi:[0,1]
	v_pk_mul_f32 v[84:85], v[190:191], v[190:191]
	v_pk_mul_f32 v[86:87], v[194:195], v[194:195]
	v_pk_mul_f32 v[80:81], v[198:199], v[198:199]
	v_pk_mul_f32 v[82:83], v[192:193], v[192:193]
	v_add_f32_e32 v87, v86, v87
	v_add_f32_e32 v85, v84, v85
	v_mov_b32_e32 v86, v82
	v_mov_b32_e32 v84, v83
	v_mov_b32_e32 v92, v80
	v_mov_b32_e32 v88, v81
	v_pk_add_f32 v[82:83], v[86:87], v[84:85]
	v_pk_add_f32 v[80:81], v[92:93], v[88:89]
	v_pk_mul_f32 v[202:203], v[124:125], v[202:203]
	v_pk_add_f32 v[80:81], v[82:83], v[80:81]
	v_pk_mul_f32 v[138:139], v[120:121], v[138:139]
	v_add_f32_e32 v86, v80, v81
	ds_bpermute_b32 v87, v181, v86
	v_pk_mul_f32 v[80:81], v[168:169], v[202:203] op_sel_hi:[0,1]
	v_pk_mul_f32 v[200:201], v[126:127], v[200:201]
	v_pk_mul_f32 v[82:83], v[168:169], v[138:139] op_sel_hi:[0,1]
	v_cvt_pk_bf16_f32 v80, v80, v81
	s_waitcnt lgkmcnt(0)
	v_add_f32_e32 v86, v86, v87
	ds_bpermute_b32 v87, v185, v86
	v_pk_mul_f32 v[114:115], v[168:169], v[200:201] op_sel_hi:[0,1]
	v_pk_mul_f32 v[84:85], v[168:169], v[196:197] op_sel_hi:[0,1]
	v_cvt_pk_bf16_f32 v81, v114, v115
	v_cvt_pk_bf16_f32 v82, v82, v83
	v_cvt_pk_bf16_f32 v83, v84, v85
	s_waitcnt vmcnt(3)
	v_pk_mul_f32 v[102:103], v[156:157], v[102:103]
	global_store_dwordx4 v[112:113], v[80:83], off sc1
	s_nop 2
	s_waitcnt lgkmcnt(0)
	v_add_f32_e32 v80, v86, v87
	v_fmamk_f32 v80, v80, 0x3c800000, v241
	v_rsq_f32_e32 v112, v80
	global_load_dwordx4 v[80:83], v189, s[84:85] offset:3120
	global_load_dwordx4 v[84:87], v189, s[84:85] offset:3104
	global_load_dwordx4 v[88:91], v189, s[84:85] offset:3088
	global_load_dwordx4 v[92:95], v189, s[84:85] offset:3072
	v_pk_mul_f32 v[100:101], v[154:155], v[100:101]
	v_pk_mul_f32 v[98:99], v[156:157], v[98:99]
	v_pk_mul_f32 v[114:115], v[118:119], v[112:113] op_sel_hi:[1,0]
	v_pk_mul_f32 v[116:117], v[116:117], v[112:113] op_sel_hi:[1,0]
	v_pk_mul_f32 v[114:115], v[132:133], v[114:115]
	v_pk_mul_f32 v[116:117], v[134:135], v[116:117]
	v_pk_mul_f32 v[118:119], v[142:143], v[112:113] op_sel_hi:[1,0]
	v_pk_mul_f32 v[138:139], v[140:141], v[112:113] op_sel_hi:[1,0]
	v_pk_mul_f32 v[140:141], v[190:191], v[112:113] op_sel_hi:[1,0]
	v_pk_mul_f32 v[142:143], v[194:195], v[112:113] op_sel_hi:[1,0]
	v_pk_mul_f32 v[190:191], v[198:199], v[112:113] op_sel_hi:[1,0]
	v_pk_mul_f32 v[112:113], v[192:193], v[112:113] op_sel_hi:[1,0]
	ds_bpermute_b32 v192, v181, v114
	ds_bpermute_b32 v193, v181, v115
	ds_bpermute_b32 v194, v181, v116
	ds_bpermute_b32 v195, v181, v117
	v_pk_mul_f32 v[138:139], v[130:131], v[138:139]
	v_pk_mul_f32 v[118:119], v[128:129], v[118:119]
	s_waitcnt vmcnt(6)
	v_pk_mul_f32 v[108:109], v[108:109], v[114:115]
	v_pk_mul_f32 v[110:111], v[110:111], v[116:117]
	s_waitcnt lgkmcnt(2)
	v_pk_fma_f32 v[100:101], v[100:101], v[192:193], v[108:109]
	s_waitcnt lgkmcnt(0)
	v_pk_fma_f32 v[102:103], v[102:103], v[194:195], v[110:111]
	ds_bpermute_b32 v108, v181, v118
	ds_bpermute_b32 v109, v181, v119
	ds_bpermute_b32 v110, v181, v138
	ds_bpermute_b32 v111, v181, v139
	v_pk_mul_f32 v[104:105], v[104:105], v[118:119]
	v_pk_mul_f32 v[106:107], v[106:107], v[138:139]
	v_pk_mul_f32 v[96:97], v[154:155], v[96:97]
	v_cndmask_b32_e64 v101, v115, v101, s[40:41]
	s_waitcnt lgkmcnt(0)
	v_pk_fma_f32 v[98:99], v[98:99], v[110:111], v[106:107]
	v_pk_fma_f32 v[96:97], v[96:97], v[108:109], v[104:105]
	v_lshl_add_u64 v[104:105], v[186:187], 0, s[20:21]
	v_cndmask_b32_e64 v100, v114, v100, s[40:41]
	v_cndmask_b32_e64 v103, v117, v103, s[40:41]
	v_cndmask_b32_e64 v102, v116, v102, s[40:41]
	v_cndmask_b32_e64 v97, v119, v97, s[40:41]
	v_cndmask_b32_e64 v96, v118, v96, s[40:41]
	v_cndmask_b32_e64 v99, v139, v99, s[40:41]
	v_cndmask_b32_e64 v98, v138, v98, s[40:41]
	v_lshlrev_b64 v[104:105], 7, v[104:105]
	v_lshl_add_u64 v[104:105], v[136:137], 0, v[104:105]
	v_pk_mul_f32 v[102:103], v[168:169], v[102:103] op_sel_hi:[0,1]
	v_pk_mul_f32 v[100:101], v[168:169], v[100:101] op_sel_hi:[0,1]
	v_pk_mul_f32 v[106:107], v[168:169], v[98:99] op_sel_hi:[0,1]
	v_pk_mul_f32 v[98:99], v[168:169], v[96:97] op_sel_hi:[0,1]
	v_cvt_pk_bf16_f32 v96, v100, v101
	v_cvt_pk_bf16_f32 v97, v102, v103
	v_cvt_pk_bf16_f32 v98, v98, v99
	v_cvt_pk_bf16_f32 v99, v106, v107
	v_pk_mul_f32 v[114:115], v[68:69], v[188:189] op_sel_hi:[1,0]
	global_store_dwordx4 v[104:105], v[96:99], off sc1
	s_nop 2
	v_lshl_add_u64 v[96:97], v[104:105], 0, 64
	v_pk_mul_f32 v[104:105], v[76:77], v[188:189] op_sel_hi:[1,0]
	v_pk_mul_f32 v[76:77], v[78:79], v[78:79]
	v_pk_mul_f32 v[106:107], v[104:105], v[104:105]
	v_pk_mul_f32 v[116:117], v[66:67], v[188:189] op_sel_hi:[1,0]
	v_pk_mov_b32 v[108:109], v[106:107], v[76:77] op_sel:[1,0]
	v_mov_b32_e32 v107, v77
	v_pk_add_f32 v[76:77], v[108:109], v[106:107]
	v_pk_mul_f32 v[106:107], v[74:75], v[188:189] op_sel_hi:[1,0]
	v_pk_mul_f32 v[108:109], v[72:73], v[188:189] op_sel_hi:[1,0]
	v_pk_mul_f32 v[72:73], v[106:107], v[106:107]
	v_pk_mul_f32 v[74:75], v[108:109], v[108:109]
	v_pk_mul_f32 v[118:119], v[64:65], v[188:189] op_sel_hi:[1,0]
	v_pk_mov_b32 v[110:111], v[74:75], v[72:73] op_sel:[1,0]
	v_mov_b32_e32 v75, v73
	v_pk_add_f32 v[72:73], v[110:111], v[74:75]
	v_pk_mul_f32 v[110:111], v[70:71], v[188:189] op_sel_hi:[1,0]
	v_pk_add_f32 v[76:77], v[76:77], v[76:77] op_sel_hi:[0,1]
	v_pk_add_f32 v[72:73], v[72:73], v[72:73] op_sel_hi:[0,1]
	v_pk_mul_f32 v[68:69], v[110:111], v[110:111]
	v_pk_mul_f32 v[70:71], v[114:115], v[114:115]
	v_pk_mul_f32 v[64:65], v[116:117], v[116:117]
	v_pk_mul_f32 v[66:67], v[118:119], v[118:119]
	v_add_f32_e32 v71, v70, v71
	v_add_f32_e32 v69, v68, v69
	v_mov_b32_e32 v70, v66
	v_mov_b32_e32 v68, v67
	v_mov_b32_e32 v76, v64
	v_mov_b32_e32 v72, v65
	v_pk_add_f32 v[66:67], v[70:71], v[68:69]
	v_pk_add_f32 v[64:65], v[76:77], v[72:73]
	v_pk_mul_f32 v[142:143], v[124:125], v[142:143]
	v_pk_add_f32 v[64:65], v[66:67], v[64:65]
	v_pk_mul_f32 v[140:141], v[126:127], v[140:141]
	v_add_f32_e32 v68, v64, v65
	ds_bpermute_b32 v69, v181, v68
	v_pk_mul_f32 v[112:113], v[120:121], v[112:113]
	v_pk_mul_f32 v[190:191], v[122:123], v[190:191]
	v_pk_mul_f32 v[98:99], v[168:169], v[140:141] op_sel_hi:[0,1]
	v_pk_mul_f32 v[100:101], v[168:169], v[142:143] op_sel_hi:[0,1]
	s_waitcnt lgkmcnt(0)
	v_add_f32_e32 v68, v68, v69
	ds_bpermute_b32 v69, v185, v68
	v_pk_mul_f32 v[66:67], v[168:169], v[112:113] op_sel_hi:[0,1]
	v_cvt_pk_bf16_f32 v64, v100, v101
	v_cvt_pk_bf16_f32 v65, v98, v99
	v_pk_mul_f32 v[102:103], v[168:169], v[190:191] op_sel_hi:[0,1]
	v_cvt_pk_bf16_f32 v66, v66, v67
	v_cvt_pk_bf16_f32 v67, v102, v103
	s_waitcnt vmcnt(3)
	v_pk_mul_f32 v[86:87], v[156:157], v[86:87]
	global_store_dwordx4 v[96:97], v[64:67], off sc1
	s_nop 2
	s_waitcnt lgkmcnt(0)
	v_add_f32_e32 v65, v68, v69
	v_lshlrev_b32_e32 v64, 6, v178
	v_fmamk_f32 v65, v65, 0x3c800000, v241
	v_and_b32_e32 v64, 0x3f3c0, v64
	v_rsq_f32_e32 v100, v65
	global_load_dwordx4 v[66:69], v64, s[84:85] offset:48
	global_load_dwordx4 v[70:73], v64, s[84:85] offset:32
	global_load_dwordx4 v[74:77], v64, s[84:85] offset:16
	global_load_dwordx4 v[96:99], v64, s[84:85]
	v_pk_mul_f32 v[84:85], v[154:155], v[84:85]
	v_pk_mul_f32 v[82:83], v[156:157], v[82:83]
	v_pk_mul_f32 v[78:79], v[78:79], v[100:101] op_sel_hi:[1,0]
	v_pk_mul_f32 v[102:103], v[104:105], v[100:101] op_sel_hi:[1,0]
	v_pk_mul_f32 v[78:79], v[134:135], v[78:79]
	v_pk_mul_f32 v[102:103], v[132:133], v[102:103]
	v_pk_mul_f32 v[112:113], v[116:117], v[100:101] op_sel_hi:[1,0]
	ds_bpermute_b32 v116, v181, v78
	ds_bpermute_b32 v117, v181, v79
	v_pk_mul_f32 v[104:105], v[108:109], v[100:101] op_sel_hi:[1,0]
	v_pk_mul_f32 v[108:109], v[110:111], v[100:101] op_sel_hi:[1,0]
	v_pk_mul_f32 v[110:111], v[114:115], v[100:101] op_sel_hi:[1,0]
	ds_bpermute_b32 v114, v181, v102
	ds_bpermute_b32 v115, v181, v103
	v_pk_mul_f32 v[106:107], v[106:107], v[100:101] op_sel_hi:[1,0]
	s_waitcnt vmcnt(6)
	v_pk_mul_f32 v[94:95], v[94:95], v[78:79]
	v_pk_mul_f32 v[106:107], v[130:131], v[106:107]
	v_pk_mul_f32 v[104:105], v[128:129], v[104:105]
	v_pk_mul_f32 v[92:93], v[92:93], v[102:103]
	s_waitcnt lgkmcnt(2)
	v_pk_fma_f32 v[86:87], v[86:87], v[116:117], v[94:95]
	s_waitcnt lgkmcnt(0)
	v_pk_fma_f32 v[84:85], v[84:85], v[114:115], v[92:93]
	v_cndmask_b32_e64 v79, v79, v87, s[40:41]
	v_cndmask_b32_e64 v78, v78, v86, s[40:41]
	ds_bpermute_b32 v86, v181, v104
	ds_bpermute_b32 v87, v181, v105
	ds_bpermute_b32 v92, v181, v106
	ds_bpermute_b32 v93, v181, v107
	v_pk_mul_f32 v[88:89], v[88:89], v[104:105]
	v_pk_mul_f32 v[90:91], v[90:91], v[106:107]
	v_pk_mul_f32 v[80:81], v[154:155], v[80:81]
	v_cndmask_b32_e64 v85, v103, v85, s[40:41]
	s_waitcnt lgkmcnt(0)
	v_pk_fma_f32 v[82:83], v[82:83], v[92:93], v[90:91]
	v_pk_fma_f32 v[80:81], v[80:81], v[86:87], v[88:89]
	v_cndmask_b32_e64 v84, v102, v84, s[40:41]
	v_cndmask_b32_e64 v81, v105, v81, s[40:41]
	v_cndmask_b32_e64 v80, v104, v80, s[40:41]
	v_cndmask_b32_e64 v83, v107, v83, s[40:41]
	v_cndmask_b32_e64 v82, v106, v82, s[40:41]
	v_lshl_add_u64 v[86:87], v[182:183], 0, s[20:21]
	v_pk_mul_f32 v[88:89], v[168:169], v[78:79] op_sel_hi:[0,1]
	v_pk_mul_f32 v[78:79], v[168:169], v[84:85] op_sel_hi:[0,1]
	v_pk_mul_f32 v[82:83], v[168:169], v[82:83] op_sel_hi:[0,1]
	v_pk_mul_f32 v[80:81], v[168:169], v[80:81] op_sel_hi:[0,1]
	v_lshlrev_b64 v[86:87], 7, v[86:87]
	v_cvt_pk_bf16_f32 v78, v78, v79
	v_cvt_pk_bf16_f32 v79, v88, v89
	v_cvt_pk_bf16_f32 v80, v80, v81
	v_cvt_pk_bf16_f32 v81, v82, v83
	v_pk_mul_f32 v[82:83], v[62:63], v[184:185] op_sel_hi:[1,0]
	v_pk_mul_f32 v[84:85], v[60:61], v[184:185] op_sel_hi:[1,0]
	v_lshl_add_u64 v[86:87], v[136:137], 0, v[86:87]
	v_pk_mul_f32 v[60:61], v[82:83], v[82:83]
	v_pk_mul_f32 v[62:63], v[84:85], v[84:85]
	global_store_dwordx4 v[86:87], v[78:81], off sc1
	s_nop 2
	v_lshl_add_u64 v[78:79], v[86:87], 0, 64
	v_pk_mov_b32 v[86:87], v[62:63], v[60:61] op_sel:[1,0]
	v_mov_b32_e32 v63, v61
	v_pk_add_f32 v[60:61], v[86:87], v[62:63]
	v_pk_mul_f32 v[86:87], v[58:59], v[184:185] op_sel_hi:[1,0]
	v_pk_mul_f32 v[88:89], v[56:57], v[184:185] op_sel_hi:[1,0]
	v_pk_mul_f32 v[56:57], v[86:87], v[86:87]
	v_pk_mul_f32 v[58:59], v[88:89], v[88:89]
	v_pk_mul_f32 v[90:91], v[54:55], v[184:185] op_sel_hi:[1,0]
	v_pk_mov_b32 v[62:63], v[58:59], v[56:57] op_sel:[1,0]
	v_mov_b32_e32 v59, v57
	v_pk_add_f32 v[56:57], v[62:63], v[58:59]
	v_pk_mul_f32 v[92:93], v[52:53], v[184:185] op_sel_hi:[1,0]
	v_pk_mul_f32 v[94:95], v[50:51], v[184:185] op_sel_hi:[1,0]
	v_pk_mul_f32 v[102:103], v[48:49], v[184:185] op_sel_hi:[1,0]
	v_pk_add_f32 v[60:61], v[60:61], v[60:61] op_sel_hi:[0,1]
	v_pk_add_f32 v[56:57], v[56:57], v[56:57] op_sel_hi:[0,1]
	v_pk_mul_f32 v[52:53], v[90:91], v[90:91]
	v_pk_mul_f32 v[54:55], v[92:93], v[92:93]
	v_pk_mul_f32 v[48:49], v[94:95], v[94:95]
	v_pk_mul_f32 v[50:51], v[102:103], v[102:103]
	v_add_f32_e32 v55, v54, v55
	v_add_f32_e32 v53, v52, v53
	v_mov_b32_e32 v54, v50
	v_mov_b32_e32 v52, v51
	v_mov_b32_e32 v60, v48
	v_mov_b32_e32 v56, v49
	v_pk_add_f32 v[50:51], v[54:55], v[52:53]
	v_pk_add_f32 v[48:49], v[60:61], v[56:57]
	v_pk_mul_f32 v[110:111], v[124:125], v[110:111]
	v_pk_add_f32 v[48:49], v[50:51], v[48:49]
	v_pk_mul_f32 v[100:101], v[118:119], v[100:101] op_sel_hi:[1,0]
	v_add_f32_e32 v54, v48, v49
	ds_bpermute_b32 v55, v181, v54
	v_pk_mul_f32 v[100:101], v[120:121], v[100:101]
	v_pk_mul_f32 v[48:49], v[168:169], v[110:111] op_sel_hi:[0,1]
	v_pk_mul_f32 v[108:109], v[126:127], v[108:109]
	v_pk_mul_f32 v[112:113], v[122:123], v[112:113]
	s_waitcnt lgkmcnt(0)
	v_add_f32_e32 v54, v54, v55
	ds_bpermute_b32 v55, v185, v54
	v_pk_mul_f32 v[50:51], v[168:169], v[100:101] op_sel_hi:[0,1]
	v_cvt_pk_bf16_f32 v48, v48, v49
	v_pk_mul_f32 v[80:81], v[168:169], v[108:109] op_sel_hi:[0,1]
	v_pk_mul_f32 v[52:53], v[168:169], v[112:113] op_sel_hi:[0,1]
	v_cvt_pk_bf16_f32 v49, v80, v81
	v_cvt_pk_bf16_f32 v50, v50, v51
	v_cvt_pk_bf16_f32 v51, v52, v53
	s_waitcnt vmcnt(3)
	v_pk_mul_f32 v[72:73], v[156:157], v[72:73]
	global_store_dwordx4 v[78:79], v[48:51], off sc1
	s_nop 2
	s_waitcnt lgkmcnt(0)
	v_add_f32_e32 v48, v54, v55
	v_fmamk_f32 v48, v48, 0x3c800000, v241
	v_rsq_f32_e32 v78, v48
	global_load_dwordx4 v[48:51], v64, s[84:85] offset:1072
	global_load_dwordx4 v[52:55], v64, s[84:85] offset:1056
	global_load_dwordx4 v[56:59], v64, s[84:85] offset:1040
	global_load_dwordx4 v[60:63], v64, s[84:85] offset:1024
	v_pk_mul_f32 v[70:71], v[154:155], v[70:71]
	v_pk_mul_f32 v[68:69], v[156:157], v[68:69]
	v_pk_mul_f32 v[80:81], v[84:85], v[78:79] op_sel_hi:[1,0]
	v_pk_mul_f32 v[82:83], v[82:83], v[78:79] op_sel_hi:[1,0]
	v_pk_mul_f32 v[80:81], v[132:133], v[80:81]
	v_pk_mul_f32 v[82:83], v[134:135], v[82:83]
	v_pk_mul_f32 v[84:85], v[88:89], v[78:79] op_sel_hi:[1,0]
	v_pk_mul_f32 v[88:89], v[90:91], v[78:79] op_sel_hi:[1,0]
	v_pk_mul_f32 v[90:91], v[92:93], v[78:79] op_sel_hi:[1,0]
	v_pk_mul_f32 v[92:93], v[94:95], v[78:79] op_sel_hi:[1,0]
	ds_bpermute_b32 v94, v181, v80
	ds_bpermute_b32 v95, v181, v81
	ds_bpermute_b32 v100, v181, v82
	ds_bpermute_b32 v101, v181, v83
	v_pk_mul_f32 v[86:87], v[86:87], v[78:79] op_sel_hi:[1,0]
	s_waitcnt vmcnt(6)
	v_pk_mul_f32 v[96:97], v[96:97], v[80:81]
	v_pk_mul_f32 v[98:99], v[98:99], v[82:83]
	v_pk_mul_f32 v[86:87], v[130:131], v[86:87]
	v_pk_mul_f32 v[84:85], v[128:129], v[84:85]
	s_waitcnt lgkmcnt(0)
	v_pk_fma_f32 v[72:73], v[72:73], v[100:101], v[98:99]
	v_pk_fma_f32 v[70:71], v[70:71], v[94:95], v[96:97]
	v_cndmask_b32_e64 v73, v83, v73, s[40:41]
	v_cndmask_b32_e64 v71, v81, v71, s[40:41]
	v_cndmask_b32_e64 v70, v80, v70, s[40:41]
	v_cndmask_b32_e64 v72, v82, v72, s[40:41]
	ds_bpermute_b32 v80, v181, v84
	ds_bpermute_b32 v81, v181, v85
	ds_bpermute_b32 v82, v181, v86
	ds_bpermute_b32 v83, v181, v87
	v_pk_mul_f32 v[74:75], v[74:75], v[84:85]
	v_pk_mul_f32 v[76:77], v[76:77], v[86:87]
	v_pk_mul_f32 v[66:67], v[154:155], v[66:67]
	v_pk_mul_f32 v[72:73], v[168:169], v[72:73] op_sel_hi:[0,1]
	s_waitcnt lgkmcnt(0)
	v_pk_fma_f32 v[68:69], v[68:69], v[82:83], v[76:77]
	v_pk_fma_f32 v[66:67], v[66:67], v[80:81], v[74:75]
	v_cndmask_b32_e64 v69, v87, v69, s[40:41]
	v_cndmask_b32_e64 v67, v85, v67, s[40:41]
	v_cndmask_b32_e64 v66, v84, v66, s[40:41]
	v_cndmask_b32_e64 v68, v86, v68, s[40:41]
	v_lshl_add_u64 v[74:75], v[178:179], 0, s[20:21]
	v_pk_mul_f32 v[70:71], v[168:169], v[70:71] op_sel_hi:[0,1]
	v_lshlrev_b64 v[74:75], 7, v[74:75]
	v_pk_mul_f32 v[76:77], v[168:169], v[68:69] op_sel_hi:[0,1]
	v_pk_mul_f32 v[68:69], v[168:169], v[66:67] op_sel_hi:[0,1]
	v_cvt_pk_bf16_f32 v66, v70, v71
	v_cvt_pk_bf16_f32 v67, v72, v73
	v_pk_mul_f32 v[70:71], v[46:47], v[180:181] op_sel_hi:[1,0]
	v_pk_mul_f32 v[72:73], v[44:45], v[180:181] op_sel_hi:[1,0]
	v_lshl_add_u64 v[74:75], v[136:137], 0, v[74:75]
	v_pk_mul_f32 v[44:45], v[70:71], v[70:71]
	v_pk_mul_f32 v[46:47], v[72:73], v[72:73]
	v_cvt_pk_bf16_f32 v68, v68, v69
	v_cvt_pk_bf16_f32 v69, v76, v77
	v_pk_mul_f32 v[76:77], v[40:41], v[180:181] op_sel_hi:[1,0]
	global_store_dwordx4 v[74:75], v[66:69], off sc1
	s_nop 2
	v_lshl_add_u64 v[66:67], v[74:75], 0, 64
	v_pk_mov_b32 v[74:75], v[46:47], v[44:45] op_sel:[1,0]
	v_mov_b32_e32 v47, v45
	v_pk_add_f32 v[44:45], v[74:75], v[46:47]
	v_pk_mul_f32 v[74:75], v[42:43], v[180:181] op_sel_hi:[1,0]
	v_pk_mul_f32 v[42:43], v[76:77], v[76:77]
	v_pk_mul_f32 v[40:41], v[74:75], v[74:75]
	v_pk_mul_f32 v[80:81], v[38:39], v[180:181] op_sel_hi:[1,0]
	v_pk_mov_b32 v[46:47], v[42:43], v[40:41] op_sel:[1,0]
	v_mov_b32_e32 v43, v41
	v_pk_add_f32 v[40:41], v[46:47], v[42:43]
	v_pk_mul_f32 v[82:83], v[36:37], v[180:181] op_sel_hi:[1,0]
	v_pk_mul_f32 v[84:85], v[34:35], v[180:181] op_sel_hi:[1,0]
	v_pk_mul_f32 v[86:87], v[32:33], v[180:181] op_sel_hi:[1,0]
	v_pk_add_f32 v[44:45], v[44:45], v[44:45] op_sel_hi:[0,1]
	v_pk_add_f32 v[40:41], v[40:41], v[40:41] op_sel_hi:[0,1]
	v_pk_mul_f32 v[36:37], v[80:81], v[80:81]
	v_pk_mul_f32 v[38:39], v[82:83], v[82:83]
	v_pk_mul_f32 v[32:33], v[84:85], v[84:85]
	v_pk_mul_f32 v[34:35], v[86:87], v[86:87]
	v_add_f32_e32 v39, v38, v39
	v_add_f32_e32 v37, v36, v37
	v_mov_b32_e32 v38, v34
	v_mov_b32_e32 v36, v35
	v_mov_b32_e32 v44, v32
	v_mov_b32_e32 v40, v33
	v_pk_add_f32 v[34:35], v[38:39], v[36:37]
	v_pk_add_f32 v[32:33], v[44:45], v[40:41]
	v_pk_mul_f32 v[90:91], v[124:125], v[90:91]
	v_pk_add_f32 v[32:33], v[34:35], v[32:33]
	v_pk_mul_f32 v[78:79], v[102:103], v[78:79] op_sel_hi:[1,0]
	v_add_f32_e32 v38, v32, v33
	ds_bpermute_b32 v39, v181, v38
	v_pk_mul_f32 v[78:79], v[120:121], v[78:79]
	v_pk_mul_f32 v[32:33], v[168:169], v[90:91] op_sel_hi:[0,1]
	v_pk_mul_f32 v[88:89], v[126:127], v[88:89]
	v_pk_mul_f32 v[92:93], v[122:123], v[92:93]
	s_waitcnt lgkmcnt(0)
	v_add_f32_e32 v38, v38, v39
	ds_bpermute_b32 v39, v185, v38
	v_pk_mul_f32 v[34:35], v[168:169], v[78:79] op_sel_hi:[0,1]
	v_cvt_pk_bf16_f32 v32, v32, v33
	v_pk_mul_f32 v[68:69], v[168:169], v[88:89] op_sel_hi:[0,1]
	v_pk_mul_f32 v[36:37], v[168:169], v[92:93] op_sel_hi:[0,1]
	v_cvt_pk_bf16_f32 v33, v68, v69
	v_cvt_pk_bf16_f32 v34, v34, v35
	v_cvt_pk_bf16_f32 v35, v36, v37
	s_waitcnt vmcnt(3)
	v_pk_mul_f32 v[54:55], v[156:157], v[54:55]
	global_store_dwordx4 v[66:67], v[32:35], off sc1
	s_nop 2
	s_waitcnt lgkmcnt(0)
	v_add_f32_e32 v32, v38, v39
	v_fmamk_f32 v32, v32, 0x3c800000, v241
	v_rsq_f32_e32 v66, v32
	global_load_dwordx4 v[32:35], v64, s[84:85] offset:2096
	global_load_dwordx4 v[36:39], v64, s[84:85] offset:2080
	global_load_dwordx4 v[40:43], v64, s[84:85] offset:2064
	global_load_dwordx4 v[44:47], v64, s[84:85] offset:2048
	v_pk_mul_f32 v[52:53], v[154:155], v[52:53]
	v_pk_mul_f32 v[50:51], v[156:157], v[50:51]
	v_pk_mul_f32 v[68:69], v[72:73], v[66:67] op_sel_hi:[1,0]
	v_pk_mul_f32 v[70:71], v[70:71], v[66:67] op_sel_hi:[1,0]
	v_pk_mul_f32 v[68:69], v[132:133], v[68:69]
	v_pk_mul_f32 v[70:71], v[134:135], v[70:71]
	v_pk_mul_f32 v[72:73], v[76:77], v[66:67] op_sel_hi:[1,0]
	v_pk_mul_f32 v[76:77], v[80:81], v[66:67] op_sel_hi:[1,0]
	v_pk_mul_f32 v[78:79], v[82:83], v[66:67] op_sel_hi:[1,0]
	v_pk_mul_f32 v[80:81], v[84:85], v[66:67] op_sel_hi:[1,0]
	ds_bpermute_b32 v82, v181, v68
	ds_bpermute_b32 v83, v181, v69
	ds_bpermute_b32 v84, v181, v70
	ds_bpermute_b32 v85, v181, v71
	v_pk_mul_f32 v[74:75], v[74:75], v[66:67] op_sel_hi:[1,0]
	v_pk_mul_f32 v[72:73], v[128:129], v[72:73]
	v_pk_mul_f32 v[74:75], v[130:131], v[74:75]
	s_waitcnt vmcnt(6)
	v_pk_mul_f32 v[60:61], v[60:61], v[68:69]
	v_pk_mul_f32 v[62:63], v[62:63], v[70:71]
	s_waitcnt lgkmcnt(2)
	v_pk_fma_f32 v[52:53], v[52:53], v[82:83], v[60:61]
	s_waitcnt lgkmcnt(0)
	v_pk_fma_f32 v[54:55], v[54:55], v[84:85], v[62:63]
	ds_bpermute_b32 v60, v181, v72
	ds_bpermute_b32 v61, v181, v73
	ds_bpermute_b32 v62, v181, v74
	ds_bpermute_b32 v63, v181, v75
	v_pk_mul_f32 v[56:57], v[56:57], v[72:73]
	v_pk_mul_f32 v[58:59], v[58:59], v[74:75]
	v_pk_mul_f32 v[48:49], v[154:155], v[48:49]
	v_cndmask_b32_e64 v53, v69, v53, s[40:41]
	v_cndmask_b32_e64 v52, v68, v52, s[40:41]
	v_cndmask_b32_e64 v55, v71, v55, s[40:41]
	v_cndmask_b32_e64 v54, v70, v54, s[40:41]
	s_waitcnt lgkmcnt(0)
	v_pk_fma_f32 v[50:51], v[50:51], v[62:63], v[58:59]
	v_pk_fma_f32 v[48:49], v[48:49], v[60:61], v[56:57]
	v_cndmask_b32_e64 v51, v75, v51, s[40:41]
	v_cndmask_b32_e64 v49, v73, v49, s[40:41]
	v_cndmask_b32_e64 v48, v72, v48, s[40:41]
	v_cndmask_b32_e64 v50, v74, v50, s[40:41]
	v_lshl_add_u64 v[56:57], v[174:175], 0, s[20:21]
	v_pk_mul_f32 v[54:55], v[168:169], v[54:55] op_sel_hi:[0,1]
	v_pk_mul_f32 v[52:53], v[168:169], v[52:53] op_sel_hi:[0,1]
	v_lshlrev_b64 v[56:57], 7, v[56:57]
	v_pk_mul_f32 v[58:59], v[168:169], v[50:51] op_sel_hi:[0,1]
	v_pk_mul_f32 v[50:51], v[168:169], v[48:49] op_sel_hi:[0,1]
	v_cvt_pk_bf16_f32 v48, v52, v53
	v_cvt_pk_bf16_f32 v49, v54, v55
	v_pk_mul_f32 v[52:53], v[30:31], v[176:177] op_sel_hi:[1,0]
	v_pk_mul_f32 v[54:55], v[28:29], v[176:177] op_sel_hi:[1,0]
	v_lshl_add_u64 v[56:57], v[136:137], 0, v[56:57]
	v_pk_mul_f32 v[28:29], v[52:53], v[52:53]
	v_pk_mul_f32 v[30:31], v[54:55], v[54:55]
	v_cvt_pk_bf16_f32 v50, v50, v51
	v_cvt_pk_bf16_f32 v51, v58, v59
	v_pk_mul_f32 v[58:59], v[24:25], v[176:177] op_sel_hi:[1,0]
	global_store_dwordx4 v[56:57], v[48:51], off sc1
	s_nop 2
	v_lshl_add_u64 v[48:49], v[56:57], 0, 64
	v_pk_mov_b32 v[56:57], v[30:31], v[28:29] op_sel:[1,0]
	v_mov_b32_e32 v31, v29
	v_pk_add_f32 v[28:29], v[56:57], v[30:31]
	v_pk_mul_f32 v[56:57], v[26:27], v[176:177] op_sel_hi:[1,0]
	v_pk_mul_f32 v[26:27], v[58:59], v[58:59]
	v_pk_mul_f32 v[24:25], v[56:57], v[56:57]
	v_pk_mul_f32 v[60:61], v[22:23], v[176:177] op_sel_hi:[1,0]
	v_pk_mov_b32 v[30:31], v[26:27], v[24:25] op_sel:[1,0]
	v_mov_b32_e32 v27, v25
	v_pk_add_f32 v[24:25], v[30:31], v[26:27]
	v_pk_mul_f32 v[62:63], v[20:21], v[176:177] op_sel_hi:[1,0]
	v_pk_mul_f32 v[68:69], v[18:19], v[176:177] op_sel_hi:[1,0]
	v_pk_mul_f32 v[70:71], v[16:17], v[176:177] op_sel_hi:[1,0]
	v_pk_add_f32 v[28:29], v[28:29], v[28:29] op_sel_hi:[0,1]
	v_pk_add_f32 v[24:25], v[24:25], v[24:25] op_sel_hi:[0,1]
	v_pk_mul_f32 v[20:21], v[60:61], v[60:61]
	v_pk_mul_f32 v[22:23], v[62:63], v[62:63]
	v_pk_mul_f32 v[16:17], v[68:69], v[68:69]
	v_pk_mul_f32 v[18:19], v[70:71], v[70:71]
	v_add_f32_e32 v23, v22, v23
	v_add_f32_e32 v21, v20, v21
	v_mov_b32_e32 v22, v18
	v_mov_b32_e32 v20, v19
	v_mov_b32_e32 v28, v16
	v_mov_b32_e32 v24, v17
	v_pk_add_f32 v[18:19], v[22:23], v[20:21]
	v_pk_add_f32 v[16:17], v[28:29], v[24:25]
	v_pk_mul_f32 v[78:79], v[124:125], v[78:79]
	v_pk_add_f32 v[16:17], v[18:19], v[16:17]
	v_pk_mul_f32 v[66:67], v[86:87], v[66:67] op_sel_hi:[1,0]
	v_add_f32_e32 v22, v16, v17
	ds_bpermute_b32 v23, v181, v22
	v_pk_mul_f32 v[66:67], v[120:121], v[66:67]
	v_pk_mul_f32 v[16:17], v[168:169], v[78:79] op_sel_hi:[0,1]
	v_pk_mul_f32 v[76:77], v[126:127], v[76:77]
	v_pk_mul_f32 v[80:81], v[122:123], v[80:81]
	s_waitcnt lgkmcnt(0)
	v_add_f32_e32 v22, v22, v23
	ds_bpermute_b32 v23, v185, v22
	v_pk_mul_f32 v[18:19], v[168:169], v[66:67] op_sel_hi:[0,1]
	v_cvt_pk_bf16_f32 v16, v16, v17
	v_pk_mul_f32 v[50:51], v[168:169], v[76:77] op_sel_hi:[0,1]
	v_pk_mul_f32 v[20:21], v[168:169], v[80:81] op_sel_hi:[0,1]
	v_cvt_pk_bf16_f32 v17, v50, v51
	v_cvt_pk_bf16_f32 v18, v18, v19
	v_cvt_pk_bf16_f32 v19, v20, v21
	s_waitcnt vmcnt(3)
	v_pk_mul_f32 v[38:39], v[156:157], v[38:39]
	global_store_dwordx4 v[48:49], v[16:19], off sc1
	s_nop 2
	s_waitcnt lgkmcnt(0)
	v_add_f32_e32 v16, v22, v23
	v_fmamk_f32 v16, v16, 0x3c800000, v241
	v_rsq_f32_e32 v48, v16
	global_load_dwordx4 v[16:19], v64, s[84:85] offset:3120
	global_load_dwordx4 v[20:23], v64, s[84:85] offset:3104
	global_load_dwordx4 v[24:27], v64, s[84:85] offset:3088
	global_load_dwordx4 v[28:31], v64, s[84:85] offset:3072
	v_pk_mul_f32 v[36:37], v[154:155], v[36:37]
	v_pk_mul_f32 v[34:35], v[156:157], v[34:35]
	v_pk_mul_f32 v[50:51], v[54:55], v[48:49] op_sel_hi:[1,0]
	v_pk_mul_f32 v[52:53], v[52:53], v[48:49] op_sel_hi:[1,0]
	v_pk_mul_f32 v[50:51], v[132:133], v[50:51]
	v_pk_mul_f32 v[52:53], v[134:135], v[52:53]
	ds_bpermute_b32 v64, v181, v50
	ds_bpermute_b32 v65, v181, v51
	ds_bpermute_b32 v66, v181, v52
	ds_bpermute_b32 v67, v181, v53
	v_pk_mul_f32 v[54:55], v[58:59], v[48:49] op_sel_hi:[1,0]
	v_pk_mul_f32 v[56:57], v[56:57], v[48:49] op_sel_hi:[1,0]
	v_pk_mul_f32 v[54:55], v[128:129], v[54:55]
	v_pk_mul_f32 v[56:57], v[130:131], v[56:57]
	s_waitcnt vmcnt(6)
	v_pk_mul_f32 v[44:45], v[44:45], v[50:51]
	v_pk_mul_f32 v[46:47], v[46:47], v[52:53]
	s_waitcnt lgkmcnt(2)
	v_pk_fma_f32 v[36:37], v[36:37], v[64:65], v[44:45]
	s_waitcnt lgkmcnt(0)
	v_pk_fma_f32 v[38:39], v[38:39], v[66:67], v[46:47]
	ds_bpermute_b32 v44, v181, v54
	ds_bpermute_b32 v45, v181, v55
	ds_bpermute_b32 v46, v181, v56
	ds_bpermute_b32 v47, v181, v57
	v_pk_mul_f32 v[40:41], v[40:41], v[54:55]
	v_pk_mul_f32 v[42:43], v[42:43], v[56:57]
	v_pk_mul_f32 v[32:33], v[154:155], v[32:33]
	v_cndmask_b32_e64 v37, v51, v37, s[40:41]
	v_cndmask_b32_e64 v36, v50, v36, s[40:41]
	v_cndmask_b32_e64 v39, v53, v39, s[40:41]
	v_cndmask_b32_e64 v38, v52, v38, s[40:41]
	s_waitcnt lgkmcnt(0)
	v_pk_fma_f32 v[34:35], v[34:35], v[46:47], v[42:43]
	v_pk_fma_f32 v[32:33], v[32:33], v[44:45], v[40:41]
	v_cndmask_b32_e64 v35, v57, v35, s[40:41]
	v_cndmask_b32_e64 v33, v55, v33, s[40:41]
	v_cndmask_b32_e64 v32, v54, v32, s[40:41]
	v_cndmask_b32_e64 v34, v56, v34, s[40:41]
	v_pk_mul_f32 v[38:39], v[168:169], v[38:39] op_sel_hi:[0,1]
	v_pk_mul_f32 v[36:37], v[168:169], v[36:37] op_sel_hi:[0,1]
	v_pk_mul_f32 v[42:43], v[168:169], v[34:35] op_sel_hi:[0,1]
	v_pk_mul_f32 v[34:35], v[168:169], v[32:33] op_sel_hi:[0,1]
	v_cvt_pk_bf16_f32 v32, v36, v37
	v_cvt_pk_bf16_f32 v33, v38, v39
	v_pk_mul_f32 v[36:37], v[14:15], v[14:15]
	v_pk_mul_f32 v[38:39], v[12:13], v[12:13]
	v_cvt_pk_bf16_f32 v34, v34, v35
	v_cvt_pk_bf16_f32 v35, v42, v43
	v_pk_mul_f32 v[46:47], v[2:3], v[172:173] op_sel_hi:[1,0]
	v_pk_mov_b32 v[42:43], v[38:39], v[36:37] op_sel:[1,0]
	v_mov_b32_e32 v39, v37
	v_pk_add_f32 v[36:37], v[42:43], v[38:39]
	v_pk_mul_f32 v[38:39], v[10:11], v[10:11]
	v_pk_mul_f32 v[42:43], v[8:9], v[8:9]
	v_pk_mul_f32 v[50:51], v[0:1], v[172:173] op_sel_hi:[1,0]
	v_pk_mov_b32 v[44:45], v[42:43], v[38:39] op_sel:[1,0]
	v_mov_b32_e32 v43, v39
	v_pk_add_f32 v[38:39], v[44:45], v[42:43]
	v_pk_add_f32 v[36:37], v[36:37], v[36:37] op_sel_hi:[0,1]
	v_pk_add_f32 v[38:39], v[38:39], v[38:39] op_sel_hi:[0,1]
	v_pk_mul_f32 v[42:43], v[6:7], v[6:7]
	v_pk_mul_f32 v[44:45], v[4:5], v[4:5]
	v_pk_mul_f32 v[0:1], v[46:47], v[46:47]
	v_pk_mul_f32 v[2:3], v[50:51], v[50:51]
	v_add_f32_e32 v45, v44, v45
	v_add_f32_e32 v43, v42, v43
	v_mov_b32_e32 v44, v2
	v_mov_b32_e32 v42, v3
	v_mov_b32_e32 v36, v0
	v_mov_b32_e32 v38, v1
	v_pk_add_f32 v[2:3], v[44:45], v[42:43]
	v_pk_add_f32 v[0:1], v[36:37], v[38:39]
	v_pk_mul_f32 v[58:59], v[60:61], v[48:49] op_sel_hi:[1,0]
	v_pk_add_f32 v[0:1], v[2:3], v[0:1]
	v_pk_mul_f32 v[60:61], v[62:63], v[48:49] op_sel_hi:[1,0]
	v_add_f32_e32 v36, v0, v1
	ds_bpermute_b32 v37, v181, v36
	v_pk_mul_f32 v[60:61], v[124:125], v[60:61]
	v_pk_mul_f32 v[58:59], v[126:127], v[58:59]
	v_lshl_add_u64 v[40:41], v[170:171], 0, s[20:21]
	v_lshlrev_b64 v[40:41], 7, v[40:41]
	s_waitcnt lgkmcnt(0)
	v_add_f32_e32 v38, v36, v37
	ds_bpermute_b32 v39, v185, v38
	v_pk_mul_f32 v[2:3], v[168:169], v[58:59] op_sel_hi:[0,1]
	v_pk_mul_f32 v[0:1], v[168:169], v[60:61] op_sel_hi:[0,1]
	v_lshl_add_u64 v[40:41], v[136:137], 0, v[40:41]
	global_store_dwordx4 v[40:41], v[32:35], off sc1
	s_nop 2
	v_cvt_pk_bf16_f32 v0, v0, v1
	v_cvt_pk_bf16_f32 v1, v2, v3
	s_waitcnt lgkmcnt(0)
	v_add_f32_e32 v2, v38, v39
	v_fmamk_f32 v2, v2, 0x3c800000, v241
	v_rsq_f32_e32 v38, v2
	v_pk_mul_f32 v[62:63], v[68:69], v[48:49] op_sel_hi:[1,0]
	v_pk_mul_f32 v[48:49], v[70:71], v[48:49] op_sel_hi:[1,0]
	v_pk_mul_f32 v[62:63], v[122:123], v[62:63]
	v_pk_mul_f32 v[48:49], v[120:121], v[48:49]
	v_pk_mul_f32 v[34:35], v[168:169], v[62:63] op_sel_hi:[0,1]
	v_pk_mul_f32 v[36:37], v[168:169], v[48:49] op_sel_hi:[0,1]
	v_cvt_pk_bf16_f32 v2, v36, v37
	v_cvt_pk_bf16_f32 v3, v34, v35
	v_lshl_add_u64 v[32:33], v[40:41], 0, 64
	global_store_dwordx4 v[32:33], v[0:3], off sc1
	s_nop 2
	v_pk_mul_f32 v[0:1], v[12:13], v[38:39] op_sel_hi:[1,0]
	v_pk_mul_f32 v[2:3], v[14:15], v[38:39] op_sel_hi:[1,0]
	v_pk_mul_f32 v[0:1], v[132:133], v[0:1]
	v_pk_mul_f32 v[2:3], v[134:135], v[2:3]
	ds_bpermute_b32 v32, v181, v0
	ds_bpermute_b32 v33, v181, v1
	ds_bpermute_b32 v34, v181, v2
	ds_bpermute_b32 v35, v181, v3
	v_pk_mul_f32 v[8:9], v[8:9], v[38:39] op_sel_hi:[1,0]
	v_pk_mul_f32 v[10:11], v[10:11], v[38:39] op_sel_hi:[1,0]
	s_waitcnt vmcnt(2)
	v_pk_mul_f32 v[28:29], v[28:29], v[0:1]
	v_pk_mul_f32 v[30:31], v[30:31], v[2:3]
	v_pk_mul_f32 v[22:23], v[156:157], v[22:23]
	v_pk_mul_f32 v[20:21], v[154:155], v[20:21]
	v_pk_mul_f32 v[10:11], v[130:131], v[10:11]
	v_pk_mul_f32 v[8:9], v[128:129], v[8:9]
	s_waitcnt lgkmcnt(0)
	v_pk_fma_f32 v[22:23], v[22:23], v[34:35], v[30:31]
	v_pk_fma_f32 v[20:21], v[20:21], v[32:33], v[28:29]
	v_cndmask_b32_e64 v3, v3, v23, s[40:41]
	v_cndmask_b32_e64 v1, v1, v21, s[40:41]
	v_cndmask_b32_e64 v0, v0, v20, s[40:41]
	v_cndmask_b32_e64 v2, v2, v22, s[40:41]
	ds_bpermute_b32 v20, v181, v8
	ds_bpermute_b32 v21, v181, v9
	ds_bpermute_b32 v22, v181, v10
	ds_bpermute_b32 v23, v181, v11
	v_pk_mul_f32 v[24:25], v[24:25], v[8:9]
	v_pk_mul_f32 v[26:27], v[26:27], v[10:11]
	v_pk_mul_f32 v[18:19], v[156:157], v[18:19]
	v_pk_mul_f32 v[16:17], v[154:155], v[16:17]
	s_waitcnt lgkmcnt(0)
	v_pk_fma_f32 v[18:19], v[18:19], v[22:23], v[26:27]
	v_pk_fma_f32 v[16:17], v[16:17], v[20:21], v[24:25]
	v_pk_mul_f32 v[6:7], v[6:7], v[38:39] op_sel_hi:[1,0]
	v_pk_mul_f32 v[4:5], v[4:5], v[38:39] op_sel_hi:[1,0]
	v_cndmask_b32_e64 v9, v9, v17, s[40:41]
	v_cndmask_b32_e64 v8, v8, v16, s[40:41]
	v_cndmask_b32_e64 v11, v11, v19, s[40:41]
	v_cndmask_b32_e64 v10, v10, v18, s[40:41]
	v_lshl_add_u64 v[16:17], v[166:167], 0, s[20:21]
	v_pk_mul_f32 v[2:3], v[168:169], v[2:3] op_sel_hi:[0,1]
	v_pk_mul_f32 v[0:1], v[168:169], v[0:1] op_sel_hi:[0,1]
	v_pk_mul_f32 v[4:5], v[124:125], v[4:5]
	v_pk_mul_f32 v[6:7], v[126:127], v[6:7]
	v_pk_mul_f32 v[12:13], v[46:47], v[38:39] op_sel_hi:[1,0]
	v_pk_mul_f32 v[14:15], v[50:51], v[38:39] op_sel_hi:[1,0]
	v_lshlrev_b64 v[16:17], 7, v[16:17]
	v_pk_mul_f32 v[10:11], v[168:169], v[10:11] op_sel_hi:[0,1]
	v_pk_mul_f32 v[8:9], v[168:169], v[8:9] op_sel_hi:[0,1]
	v_cvt_pk_bf16_f32 v0, v0, v1
	v_cvt_pk_bf16_f32 v1, v2, v3
	v_cvt_pk_bf16_f32 v2, v8, v9
	v_cvt_pk_bf16_f32 v3, v10, v11
	v_pk_mul_f32 v[14:15], v[120:121], v[14:15]
	v_pk_mul_f32 v[12:13], v[122:123], v[12:13]
	v_lshl_add_u64 v[16:17], v[136:137], 0, v[16:17]
	global_store_dwordx4 v[16:17], v[0:3], off sc1
	s_nop 2
	v_pk_mul_f32 v[2:3], v[168:169], v[6:7] op_sel_hi:[0,1]
	v_pk_mul_f32 v[0:1], v[168:169], v[4:5] op_sel_hi:[0,1]
	v_lshl_add_u64 v[8:9], v[16:17], 0, 64
	v_pk_mul_f32 v[4:5], v[168:169], v[12:13] op_sel_hi:[0,1]
	v_pk_mul_f32 v[6:7], v[168:169], v[14:15] op_sel_hi:[0,1]
	v_cvt_pk_bf16_f32 v0, v0, v1
	v_cvt_pk_bf16_f32 v1, v2, v3
	v_cvt_pk_bf16_f32 v2, v6, v7
	v_cvt_pk_bf16_f32 v3, v4, v5
	s_nop 0
	global_store_dwordx4 v[8:9], v[0:3], off sc1
	s_nop 2
	s_andn2_b64 vcc, exec, s[42:43]
	s_mov_b64 s[28:29], -1
	s_cbranch_vccnz .LBB0_319
